# baseline (speedup 1.0000x reference)
; __device__ __forceinline__ float bflo(unsigned u) { return __uint_as_float(u << 16); }
; __device__ __forceinline__ float bfhi(unsigned u) { return __uint_as_float(u & 0xffff0000u); }
; __device__ __forceinline__ float silu(float x) { return x / (1.f + __expf(-x)); }
;   __device__ __forceinline__ bfu* z4() const { return (bfu*)(b + L::o_z4); }
; template <bool FOX, int G>
; __device__ __forceinline__ void p3_attn(const Ptrs<G>& w, int seq, int h, int qb, bfu* sm, int kslot) {
;     ...
;   const int zoff = FOX ? 1536 : 1024;
; #pragma unroll
;   for (int j = 0; j < 2; ++j) {
;     const float inv = FOX ? (1.f / lsum[j]) : 1.f;
;     const size_t row = rowbase + qrow0 + 16 * j + c15;
; #pragma unroll
;     for (int dt = 0; dt < 4; ++dt) {
;       bfu* zp = w.z4() + row * 2048 + zoff + h * 64 + 16 * dt + 4 * g;
;       uint2 zz = *(const uint2*)zp;
;       uint2 o;
;       o.x = pack2(O[dt][j][0] * inv * silu(bflo(zz.x)), O[dt][j][1] * inv * silu(bfhi(zz.x)));
;       o.y = pack2(O[dt][j][2] * inv * silu(bflo(zz.y)), O[dt][j][3] * inv * silu(bfhi(zz.y)));
;       *(uint2*)zp = o;
.LBB0_344:
	s_or_b64 exec, exec, s[96:97]
	v_readlane_b32 s12, v253, 38
	s_waitcnt vmcnt(2)
	v_lshlrev_b64 v[28:29], 12, v[100:101]
	v_readlane_b32 s14, v253, 40
	v_readlane_b32 s15, v253, 41
	s_lshl_b32 s2, s87, 1
	v_lshlrev_b32_e32 v152, 1, v99
	v_lshl_add_u64 v[28:29], s[14:15], 0, v[28:29]
	v_lshl_add_u64 v[28:29], v[28:29], 0, s[2:3]
	v_lshl_add_u64 v[28:29], v[28:29], 0, v[152:153]
	s_mov_b32 s87, 0xe122000
	v_add_co_u32_e32 v28, vcc, s87, v28
	v_readlane_b32 s54, v254, 0
	s_nop 0
	v_addc_co_u32_e32 v29, vcc, 0, v29, vcc
	global_load_dwordx2 v[30:31], v[28:29], off
	global_load_dwordx2 v[240:241], v[28:29], off offset:32
	global_load_dwordx2 v[242:243], v[28:29], off offset:64
	global_load_dwordx2 v[244:245], v[28:29], off offset:96
	v_readlane_b32 s56, v254, 2
	v_readlane_b32 s60, v254, 6
	v_readlane_b32 s62, v254, 8
	v_readlane_b32 s64, v254, 10
	v_readlane_b32 s66, v254, 12
	v_readlane_b32 s68, v254, 14
	v_readlane_b32 s70, v254, 16
	v_readlane_b32 s72, v254, 18
	v_readlane_b32 s52, v253, 62
	v_readlane_b32 s55, v254, 1
	v_readlane_b32 s57, v254, 3
	v_readlane_b32 s58, v254, 4
	v_readlane_b32 s59, v254, 5
	v_readlane_b32 s61, v254, 7
	v_readlane_b32 s63, v254, 9
	v_readlane_b32 s65, v254, 11
	v_readlane_b32 s67, v254, 13
	v_readlane_b32 s69, v254, 15
	v_readlane_b32 s71, v254, 17
	v_readlane_b32 s73, v254, 19
	v_readlane_b32 s6, v254, 49
	v_readlane_b32 s13, v253, 39
	v_readlane_b32 s53, v253, 63
	s_waitcnt vmcnt(3)
	v_lshlrev_b32_e32 v34, 16, v30
	v_and_b32_e32 v30, 0xffff0000, v30
	v_mul_f32_e32 v32, 0xbfb8aa3b, v34
	v_mul_f32_e32 v33, 0xbfb8aa3b, v30
	v_exp_f32_e32 v32, v32
	v_exp_f32_e32 v33, v33
	s_nop 0
	v_pk_add_f32 v[32:33], v[32:33], 1.0 op_sel_hi:[1,0]
	s_nop 0
	v_div_scale_f32 v35, s[0:1], v33, v33, v30
	v_rcp_f32_e32 v36, v35
	s_nop 0
	v_fma_f32 v37, -v35, v36, 1.0
	v_fmac_f32_e32 v36, v37, v36
	v_div_scale_f32 v37, vcc, v30, v33, v30
	v_mul_f32_e32 v38, v37, v36
	v_fma_f32 v39, -v35, v38, v37
	v_fmac_f32_e32 v38, v39, v36
	v_fma_f32 v35, -v35, v38, v37
	v_div_fmas_f32 v35, v35, v36, v38
	v_div_fixup_f32 v33, v35, v33, v30
	v_div_scale_f32 v30, s[0:1], v32, v32, v34
	v_rcp_f32_e32 v35, v30
	s_nop 0
	v_fma_f32 v36, -v30, v35, 1.0
	v_fmac_f32_e32 v35, v36, v35
	v_div_scale_f32 v36, vcc, v34, v32, v34
	v_mul_f32_e32 v37, v36, v35
	v_fma_f32 v38, -v30, v37, v36
	v_fmac_f32_e32 v37, v38, v35
	v_fma_f32 v30, -v30, v37, v36
	v_div_fmas_f32 v30, v30, v35, v37
	v_div_fixup_f32 v32, v30, v32, v34
	v_pk_mul_f32 v[32:33], v[60:61], v[32:33]
	v_lshlrev_b32_e32 v34, 16, v31
	v_and_b32_e32 v31, 0xffff0000, v31
	v_cvt_pk_bf16_f32 v30, v32, v33
	v_mul_f32_e32 v32, 0xbfb8aa3b, v34
	v_mul_f32_e32 v33, 0xbfb8aa3b, v31
	v_exp_f32_e32 v32, v32
	v_exp_f32_e32 v33, v33
	s_nop 0
	v_pk_add_f32 v[32:33], v[32:33], 1.0 op_sel_hi:[1,0]
	s_nop 0
	v_div_scale_f32 v35, s[0:1], v33, v33, v31
	v_rcp_f32_e32 v36, v35
	s_nop 0
	v_fma_f32 v37, -v35, v36, 1.0
	v_fmac_f32_e32 v36, v37, v36
	v_div_scale_f32 v37, vcc, v31, v33, v31
	v_mul_f32_e32 v38, v37, v36
	v_fma_f32 v39, -v35, v38, v37
	v_fmac_f32_e32 v38, v39, v36
	v_fma_f32 v35, -v35, v38, v37
	v_div_fmas_f32 v35, v35, v36, v38
	v_div_fixup_f32 v33, v35, v33, v31
	v_div_scale_f32 v31, s[0:1], v32, v32, v34
	v_rcp_f32_e32 v35, v31
	s_nop 0
	v_fma_f32 v36, -v31, v35, 1.0
	v_fmac_f32_e32 v35, v36, v35
	v_div_scale_f32 v36, vcc, v34, v32, v34
	v_mul_f32_e32 v37, v36, v35
	v_fma_f32 v38, -v31, v37, v36
	v_fmac_f32_e32 v37, v38, v35
	v_fma_f32 v31, -v31, v37, v36
	v_div_fmas_f32 v31, v31, v35, v37
	v_div_fixup_f32 v32, v31, v32, v34
	v_pk_mul_f32 v[32:33], v[62:63], v[32:33]
	s_nop 0
	v_cvt_pk_bf16_f32 v31, v32, v33
	global_store_dwordx2 v[28:29], v[30:31], off
	s_waitcnt vmcnt(3)
	v_mov_b32_e32 v30, v240
	v_mov_b32_e32 v31, v241
	v_lshlrev_b32_e32 v34, 16, v30
	v_and_b32_e32 v30, 0xffff0000, v30
	v_mul_f32_e32 v32, 0xbfb8aa3b, v34
	v_mul_f32_e32 v33, 0xbfb8aa3b, v30
	v_exp_f32_e32 v32, v32
	v_exp_f32_e32 v33, v33
	s_nop 0
	v_pk_add_f32 v[32:33], v[32:33], 1.0 op_sel_hi:[1,0]
	s_nop 0
	v_div_scale_f32 v35, s[0:1], v33, v33, v30
	v_rcp_f32_e32 v36, v35
	s_nop 0
	v_fma_f32 v37, -v35, v36, 1.0
	v_fmac_f32_e32 v36, v37, v36
	v_div_scale_f32 v37, vcc, v30, v33, v30
	v_mul_f32_e32 v38, v37, v36
	v_fma_f32 v39, -v35, v38, v37
	v_fmac_f32_e32 v38, v39, v36
	v_fma_f32 v35, -v35, v38, v37
	v_div_fmas_f32 v35, v35, v36, v38
	v_div_fixup_f32 v33, v35, v33, v30
	v_div_scale_f32 v30, s[0:1], v32, v32, v34
	v_rcp_f32_e32 v35, v30
	s_nop 0
	v_fma_f32 v36, -v30, v35, 1.0
	v_fmac_f32_e32 v35, v36, v35
	v_div_scale_f32 v36, vcc, v34, v32, v34
	v_mul_f32_e32 v37, v36, v35
	v_fma_f32 v38, -v30, v37, v36
	v_fmac_f32_e32 v37, v38, v35
	v_fma_f32 v30, -v30, v37, v36
	v_div_fmas_f32 v30, v30, v35, v37
	v_div_fixup_f32 v32, v30, v32, v34
	v_pk_mul_f32 v[24:25], v[24:25], v[32:33]
	v_and_b32_e32 v32, 0xffff0000, v31
	v_cvt_pk_bf16_f32 v24, v24, v25
	v_lshlrev_b32_e32 v25, 16, v31
	v_mul_f32_e32 v30, 0xbfb8aa3b, v25
	v_mul_f32_e32 v31, 0xbfb8aa3b, v32
	v_exp_f32_e32 v30, v30
	v_exp_f32_e32 v31, v31
	s_nop 0
	v_pk_add_f32 v[30:31], v[30:31], 1.0 op_sel_hi:[1,0]
	s_nop 0
	v_div_scale_f32 v33, s[0:1], v31, v31, v32
	v_rcp_f32_e32 v34, v33
	s_nop 0
	v_fma_f32 v35, -v33, v34, 1.0
	v_fmac_f32_e32 v34, v35, v34
	v_div_scale_f32 v35, vcc, v32, v31, v32
	v_mul_f32_e32 v36, v35, v34
	v_fma_f32 v37, -v33, v36, v35
	v_fmac_f32_e32 v36, v37, v34
	v_fma_f32 v33, -v33, v36, v35
	v_div_fmas_f32 v33, v33, v34, v36
	v_div_fixup_f32 v31, v33, v31, v32
	v_div_scale_f32 v32, s[0:1], v30, v30, v25
	v_rcp_f32_e32 v33, v32
	s_nop 0
	v_fma_f32 v34, -v32, v33, 1.0
	v_fmac_f32_e32 v33, v34, v33
	v_div_scale_f32 v34, vcc, v25, v30, v25
	v_mul_f32_e32 v35, v34, v33
	v_fma_f32 v36, -v32, v35, v34
	v_fmac_f32_e32 v35, v36, v33
	v_fma_f32 v32, -v32, v35, v34
	v_div_fmas_f32 v32, v32, v33, v35
	v_div_fixup_f32 v30, v32, v30, v25
	v_pk_mul_f32 v[26:27], v[26:27], v[30:31]
	s_nop 0
	v_cvt_pk_bf16_f32 v25, v26, v27
	global_store_dwordx2 v[28:29], v[24:25], off offset:32
	s_waitcnt vmcnt(3)
; __device__ __forceinline__ float bflo(unsigned u) { return __uint_as_float(u << 16); }
; __device__ __forceinline__ float bfhi(unsigned u) { return __uint_as_float(u & 0xffff0000u); }
; __device__ __forceinline__ float silu(float x) { return x / (1.f + __expf(-x)); }
;   __device__ __forceinline__ bfu* z4() const { return (bfu*)(b + L::o_z4); }
; template <bool FOX, int G>
; __device__ __forceinline__ void p3_attn(const Ptrs<G>& w, int seq, int h, int qb, bfu* sm, int kslot) {
;     ...
;     for (int dt = 0; dt < 4; ++dt) {
;       bfu* zp = w.z4() + row * 2048 + zoff + h * 64 + 16 * dt + 4 * g;
;       uint2 zz = *(const uint2*)zp;
;       uint2 o;
;       o.x = pack2(O[dt][j][0] * inv * silu(bflo(zz.x)), O[dt][j][1] * inv * silu(bfhi(zz.x)));
;       o.y = pack2(O[dt][j][2] * inv * silu(bflo(zz.y)), O[dt][j][3] * inv * silu(bfhi(zz.y)));
;       *(uint2*)zp = o;
	v_mov_b32_e32 v24, v242
	v_mov_b32_e32 v25, v243
	v_lshlrev_b32_e32 v30, 16, v24
	v_and_b32_e32 v24, 0xffff0000, v24
	v_mul_f32_e32 v26, 0xbfb8aa3b, v30
	v_mul_f32_e32 v27, 0xbfb8aa3b, v24
	v_exp_f32_e32 v26, v26
	v_exp_f32_e32 v27, v27
	s_nop 0
	v_pk_add_f32 v[26:27], v[26:27], 1.0 op_sel_hi:[1,0]
	s_nop 0
	v_div_scale_f32 v31, s[0:1], v27, v27, v24
	v_rcp_f32_e32 v32, v31
	s_nop 0
	v_fma_f32 v33, -v31, v32, 1.0
	v_fmac_f32_e32 v32, v33, v32
	v_div_scale_f32 v33, vcc, v24, v27, v24
	v_mul_f32_e32 v34, v33, v32
	v_fma_f32 v35, -v31, v34, v33
	v_fmac_f32_e32 v34, v35, v32
	v_fma_f32 v31, -v31, v34, v33
	v_div_fmas_f32 v31, v31, v32, v34
	v_div_fixup_f32 v27, v31, v27, v24
	v_div_scale_f32 v24, s[0:1], v26, v26, v30
	v_rcp_f32_e32 v31, v24
	s_nop 0
	v_fma_f32 v32, -v24, v31, 1.0
	v_fmac_f32_e32 v31, v32, v31
	v_div_scale_f32 v32, vcc, v30, v26, v30
	v_mul_f32_e32 v33, v32, v31
	v_fma_f32 v34, -v24, v33, v32
	v_fmac_f32_e32 v33, v34, v31
	v_fma_f32 v24, -v24, v33, v32
	v_div_fmas_f32 v24, v24, v31, v33
	v_div_fixup_f32 v26, v24, v26, v30
	v_pk_mul_f32 v[20:21], v[20:21], v[26:27]
	v_and_b32_e32 v26, 0xffff0000, v25
	v_cvt_pk_bf16_f32 v20, v20, v21
	v_lshlrev_b32_e32 v21, 16, v25
	v_mul_f32_e32 v24, 0xbfb8aa3b, v21
	v_mul_f32_e32 v25, 0xbfb8aa3b, v26
	v_exp_f32_e32 v24, v24
	v_exp_f32_e32 v25, v25
	s_nop 0
	v_pk_add_f32 v[24:25], v[24:25], 1.0 op_sel_hi:[1,0]
	s_nop 0
	v_div_scale_f32 v27, s[0:1], v25, v25, v26
	v_rcp_f32_e32 v30, v27
	s_nop 0
	v_fma_f32 v31, -v27, v30, 1.0
	v_fmac_f32_e32 v30, v31, v30
	v_div_scale_f32 v31, vcc, v26, v25, v26
	v_mul_f32_e32 v32, v31, v30
	v_fma_f32 v33, -v27, v32, v31
	v_fmac_f32_e32 v32, v33, v30
	v_fma_f32 v27, -v27, v32, v31
	v_div_fmas_f32 v27, v27, v30, v32
	v_div_fixup_f32 v25, v27, v25, v26
	v_div_scale_f32 v26, s[0:1], v24, v24, v21
	v_rcp_f32_e32 v27, v26
	s_nop 0
	v_fma_f32 v30, -v26, v27, 1.0
	v_fmac_f32_e32 v27, v30, v27
	v_div_scale_f32 v30, vcc, v21, v24, v21
	v_mul_f32_e32 v31, v30, v27
	v_fma_f32 v32, -v26, v31, v30
	v_fmac_f32_e32 v31, v32, v27
	v_fma_f32 v26, -v26, v31, v30
	v_div_fmas_f32 v26, v26, v27, v31
	v_div_fixup_f32 v24, v26, v24, v21
	v_pk_mul_f32 v[22:23], v[22:23], v[24:25]
	s_nop 0
	v_cvt_pk_bf16_f32 v21, v22, v23
	global_store_dwordx2 v[28:29], v[20:21], off offset:64
	s_waitcnt vmcnt(3)
	v_mov_b32_e32 v20, v244
	v_mov_b32_e32 v21, v245
	v_lshlrev_b32_e32 v24, 16, v20
	v_and_b32_e32 v20, 0xffff0000, v20
	v_mul_f32_e32 v22, 0xbfb8aa3b, v24
	v_mul_f32_e32 v23, 0xbfb8aa3b, v20
	v_exp_f32_e32 v22, v22
	v_exp_f32_e32 v23, v23
	s_nop 0
	v_pk_add_f32 v[22:23], v[22:23], 1.0 op_sel_hi:[1,0]
	s_nop 0
	v_div_scale_f32 v25, s[0:1], v23, v23, v20
	v_rcp_f32_e32 v26, v25
	s_nop 0
	v_fma_f32 v27, -v25, v26, 1.0
	v_fmac_f32_e32 v26, v27, v26
	v_div_scale_f32 v27, vcc, v20, v23, v20
	v_mul_f32_e32 v30, v27, v26
	v_fma_f32 v31, -v25, v30, v27
	v_fmac_f32_e32 v30, v31, v26
	v_fma_f32 v25, -v25, v30, v27
	v_div_fmas_f32 v25, v25, v26, v30
	v_div_fixup_f32 v23, v25, v23, v20
	v_div_scale_f32 v20, s[0:1], v22, v22, v24
	v_rcp_f32_e32 v25, v20
	s_nop 0
	v_fma_f32 v26, -v20, v25, 1.0
	v_fmac_f32_e32 v25, v26, v25
	v_div_scale_f32 v26, vcc, v24, v22, v24
	v_mul_f32_e32 v27, v26, v25
	v_fma_f32 v30, -v20, v27, v26
	v_fmac_f32_e32 v27, v30, v25
	v_fma_f32 v20, -v20, v27, v26
	v_div_fmas_f32 v20, v20, v25, v27
	v_div_fixup_f32 v22, v20, v22, v24
	v_pk_mul_f32 v[16:17], v[16:17], v[22:23]
	v_and_b32_e32 v22, 0xffff0000, v21
	v_cvt_pk_bf16_f32 v16, v16, v17
	v_lshlrev_b32_e32 v17, 16, v21
	v_mul_f32_e32 v20, 0xbfb8aa3b, v17
	v_mul_f32_e32 v21, 0xbfb8aa3b, v22
	v_exp_f32_e32 v20, v20
	v_exp_f32_e32 v21, v21
	s_nop 0
	v_pk_add_f32 v[20:21], v[20:21], 1.0 op_sel_hi:[1,0]
	s_nop 0
	v_div_scale_f32 v23, s[0:1], v21, v21, v22
	v_rcp_f32_e32 v24, v23
	s_nop 0
	v_fma_f32 v25, -v23, v24, 1.0
	v_fmac_f32_e32 v24, v25, v24
	v_div_scale_f32 v25, vcc, v22, v21, v22
	v_mul_f32_e32 v26, v25, v24
	v_fma_f32 v27, -v23, v26, v25
	v_fmac_f32_e32 v26, v27, v24
	v_fma_f32 v23, -v23, v26, v25
	v_div_fmas_f32 v23, v23, v24, v26
	v_div_fixup_f32 v21, v23, v21, v22
	v_div_scale_f32 v22, s[0:1], v20, v20, v17
	v_rcp_f32_e32 v23, v22
	s_nop 0
	v_fma_f32 v24, -v22, v23, 1.0
	v_fmac_f32_e32 v23, v24, v23
	v_div_scale_f32 v24, vcc, v17, v20, v17
	v_mul_f32_e32 v25, v24, v23
	v_fma_f32 v26, -v22, v25, v24
	v_fmac_f32_e32 v25, v26, v23
	v_fma_f32 v22, -v22, v25, v24
	v_div_fmas_f32 v22, v22, v23, v25
	v_div_fixup_f32 v20, v22, v20, v17
	v_pk_mul_f32 v[18:19], v[18:19], v[20:21]
	s_nop 0
	v_cvt_pk_bf16_f32 v17, v18, v19
	global_store_dwordx2 v[28:29], v[16:17], off offset:96
	v_lshlrev_b64 v[16:17], 12, v[96:97]
	v_lshl_add_u64 v[16:17], s[14:15], 0, v[16:17]
	v_lshl_add_u64 v[16:17], v[16:17], 0, s[2:3]
	v_lshl_add_u64 v[16:17], v[16:17], 0, v[152:153]
	v_add_co_u32_e32 v16, vcc, s87, v16
	s_nop 1
	v_addc_co_u32_e32 v17, vcc, 0, v17, vcc
	global_load_dwordx2 v[18:19], v[16:17], off
	global_load_dwordx2 v[240:241], v[16:17], off offset:32
	global_load_dwordx2 v[242:243], v[16:17], off offset:64
	global_load_dwordx2 v[244:245], v[16:17], off offset:96
	s_waitcnt vmcnt(3)
; __device__ __forceinline__ float bflo(unsigned u) { return __uint_as_float(u << 16); }
; __device__ __forceinline__ float bfhi(unsigned u) { return __uint_as_float(u & 0xffff0000u); }
; __device__ __forceinline__ float silu(float x) { return x / (1.f + __expf(-x)); }
;   __device__ __forceinline__ bfu* z4() const { return (bfu*)(b + L::o_z4); }
; template <bool FOX, int G>
; __device__ __forceinline__ void p3_attn(const Ptrs<G>& w, int seq, int h, int qb, bfu* sm, int kslot) {
;     ...
;     for (int dt = 0; dt < 4; ++dt) {
;       bfu* zp = w.z4() + row * 2048 + zoff + h * 64 + 16 * dt + 4 * g;
;       uint2 zz = *(const uint2*)zp;
;       uint2 o;
;       o.x = pack2(O[dt][j][0] * inv * silu(bflo(zz.x)), O[dt][j][1] * inv * silu(bfhi(zz.x)));
;       o.y = pack2(O[dt][j][2] * inv * silu(bflo(zz.y)), O[dt][j][3] * inv * silu(bfhi(zz.y)));
;       *(uint2*)zp = o;
	v_lshlrev_b32_e32 v22, 16, v18
	v_and_b32_e32 v18, 0xffff0000, v18
	v_mul_f32_e32 v20, 0xbfb8aa3b, v22
	v_mul_f32_e32 v21, 0xbfb8aa3b, v18
	v_exp_f32_e32 v20, v20
	v_exp_f32_e32 v21, v21
	s_nop 0
	v_pk_add_f32 v[20:21], v[20:21], 1.0 op_sel_hi:[1,0]
	s_nop 0
	v_div_scale_f32 v23, s[0:1], v21, v21, v18
	v_rcp_f32_e32 v24, v23
	s_nop 0
	v_fma_f32 v25, -v23, v24, 1.0
	v_fmac_f32_e32 v24, v25, v24
	v_div_scale_f32 v25, vcc, v18, v21, v18
	v_mul_f32_e32 v26, v25, v24
	v_fma_f32 v27, -v23, v26, v25
	v_fmac_f32_e32 v26, v27, v24
	v_fma_f32 v23, -v23, v26, v25
	v_div_fmas_f32 v23, v23, v24, v26
	v_div_fixup_f32 v21, v23, v21, v18
	v_div_scale_f32 v18, s[0:1], v20, v20, v22
	v_rcp_f32_e32 v23, v18
	s_nop 0
	v_fma_f32 v24, -v18, v23, 1.0
	v_fmac_f32_e32 v23, v24, v23
	v_div_scale_f32 v24, vcc, v22, v20, v22
	v_mul_f32_e32 v25, v24, v23
	v_fma_f32 v26, -v18, v25, v24
	v_fmac_f32_e32 v25, v26, v23
	v_fma_f32 v18, -v18, v25, v24
	v_div_fmas_f32 v18, v18, v23, v25
	v_div_fixup_f32 v20, v18, v20, v22
	v_pk_mul_f32 v[12:13], v[12:13], v[20:21]
	v_and_b32_e32 v20, 0xffff0000, v19
	v_cvt_pk_bf16_f32 v12, v12, v13
	v_lshlrev_b32_e32 v13, 16, v19
	v_mul_f32_e32 v18, 0xbfb8aa3b, v13
	v_mul_f32_e32 v19, 0xbfb8aa3b, v20
	v_exp_f32_e32 v18, v18
	v_exp_f32_e32 v19, v19
	s_nop 0
	v_pk_add_f32 v[18:19], v[18:19], 1.0 op_sel_hi:[1,0]
	s_nop 0
	v_div_scale_f32 v21, s[0:1], v19, v19, v20
	v_rcp_f32_e32 v22, v21
	s_nop 0
	v_fma_f32 v23, -v21, v22, 1.0
	v_fmac_f32_e32 v22, v23, v22
	v_div_scale_f32 v23, vcc, v20, v19, v20
	v_mul_f32_e32 v24, v23, v22
	v_fma_f32 v25, -v21, v24, v23
	v_fmac_f32_e32 v24, v25, v22
	v_fma_f32 v21, -v21, v24, v23
	v_div_fmas_f32 v21, v21, v22, v24
	v_div_fixup_f32 v19, v21, v19, v20
	v_div_scale_f32 v20, s[0:1], v18, v18, v13
	v_rcp_f32_e32 v21, v20
	s_nop 0
	v_fma_f32 v22, -v20, v21, 1.0
	v_fmac_f32_e32 v21, v22, v21
	v_div_scale_f32 v22, vcc, v13, v18, v13
	v_mul_f32_e32 v23, v22, v21
	v_fma_f32 v24, -v20, v23, v22
	v_fmac_f32_e32 v23, v24, v21
	v_fma_f32 v20, -v20, v23, v22
	v_div_fmas_f32 v20, v20, v21, v23
	v_div_fixup_f32 v18, v20, v18, v13
	v_pk_mul_f32 v[14:15], v[14:15], v[18:19]
	s_nop 0
	v_cvt_pk_bf16_f32 v13, v14, v15
	global_store_dwordx2 v[16:17], v[12:13], off
	s_waitcnt vmcnt(3)
	v_mov_b32_e32 v12, v240
	v_mov_b32_e32 v13, v241
	v_lshlrev_b32_e32 v18, 16, v12
	v_and_b32_e32 v12, 0xffff0000, v12
	v_mul_f32_e32 v14, 0xbfb8aa3b, v18
	v_mul_f32_e32 v15, 0xbfb8aa3b, v12
	v_exp_f32_e32 v14, v14
	v_exp_f32_e32 v15, v15
	s_nop 0
	v_pk_add_f32 v[14:15], v[14:15], 1.0 op_sel_hi:[1,0]
	s_nop 0
	v_div_scale_f32 v19, s[0:1], v15, v15, v12
	v_rcp_f32_e32 v20, v19
	s_nop 0
	v_fma_f32 v21, -v19, v20, 1.0
	v_fmac_f32_e32 v20, v21, v20
	v_div_scale_f32 v21, vcc, v12, v15, v12
	v_mul_f32_e32 v22, v21, v20
	v_fma_f32 v23, -v19, v22, v21
	v_fmac_f32_e32 v22, v23, v20
	v_fma_f32 v19, -v19, v22, v21
	v_div_fmas_f32 v19, v19, v20, v22
	v_div_fixup_f32 v15, v19, v15, v12
	v_div_scale_f32 v12, s[0:1], v14, v14, v18
	v_rcp_f32_e32 v19, v12
	s_nop 0
	v_fma_f32 v20, -v12, v19, 1.0
	v_fmac_f32_e32 v19, v20, v19
	v_div_scale_f32 v20, vcc, v18, v14, v18
	v_mul_f32_e32 v21, v20, v19
	v_fma_f32 v22, -v12, v21, v20
	v_fmac_f32_e32 v21, v22, v19
	v_fma_f32 v12, -v12, v21, v20
	v_div_fmas_f32 v12, v12, v19, v21
	v_div_fixup_f32 v14, v12, v14, v18
	v_pk_mul_f32 v[8:9], v[8:9], v[14:15]
	v_and_b32_e32 v14, 0xffff0000, v13
	v_cvt_pk_bf16_f32 v8, v8, v9
	v_lshlrev_b32_e32 v9, 16, v13
	v_mul_f32_e32 v12, 0xbfb8aa3b, v9
	v_mul_f32_e32 v13, 0xbfb8aa3b, v14
	v_exp_f32_e32 v12, v12
	v_exp_f32_e32 v13, v13
	s_nop 0
	v_pk_add_f32 v[12:13], v[12:13], 1.0 op_sel_hi:[1,0]
	s_nop 0
	v_div_scale_f32 v15, s[0:1], v13, v13, v14
	v_rcp_f32_e32 v18, v15
	s_nop 0
	v_fma_f32 v19, -v15, v18, 1.0
	v_fmac_f32_e32 v18, v19, v18
	v_div_scale_f32 v19, vcc, v14, v13, v14
	v_mul_f32_e32 v20, v19, v18
	v_fma_f32 v21, -v15, v20, v19
	v_fmac_f32_e32 v20, v21, v18
	v_fma_f32 v15, -v15, v20, v19
	v_div_fmas_f32 v15, v15, v18, v20
	v_div_fixup_f32 v13, v15, v13, v14
	v_div_scale_f32 v14, s[0:1], v12, v12, v9
	v_rcp_f32_e32 v15, v14
	s_nop 0
	v_fma_f32 v18, -v14, v15, 1.0
	v_fmac_f32_e32 v15, v18, v15
	v_div_scale_f32 v18, vcc, v9, v12, v9
	v_mul_f32_e32 v19, v18, v15
	v_fma_f32 v20, -v14, v19, v18
	v_fmac_f32_e32 v19, v20, v15
	v_fma_f32 v14, -v14, v19, v18
	v_div_fmas_f32 v14, v14, v15, v19
	v_div_fixup_f32 v12, v14, v12, v9
	v_pk_mul_f32 v[10:11], v[10:11], v[12:13]
	s_nop 0
	v_cvt_pk_bf16_f32 v9, v10, v11
	global_store_dwordx2 v[16:17], v[8:9], off offset:32
	s_waitcnt vmcnt(3)
; __device__ __forceinline__ float bflo(unsigned u) { return __uint_as_float(u << 16); }
; __device__ __forceinline__ float bfhi(unsigned u) { return __uint_as_float(u & 0xffff0000u); }
; __device__ __forceinline__ float silu(float x) { return x / (1.f + __expf(-x)); }
;   __device__ __forceinline__ bfu* z4() const { return (bfu*)(b + L::o_z4); }
; template <bool FOX, int G>
; __device__ __forceinline__ void p3_attn(const Ptrs<G>& w, int seq, int h, int qb, bfu* sm, int kslot) {
;     ...
;     for (int dt = 0; dt < 4; ++dt) {
;       bfu* zp = w.z4() + row * 2048 + zoff + h * 64 + 16 * dt + 4 * g;
;       uint2 zz = *(const uint2*)zp;
;       uint2 o;
;       o.x = pack2(O[dt][j][0] * inv * silu(bflo(zz.x)), O[dt][j][1] * inv * silu(bfhi(zz.x)));
;       o.y = pack2(O[dt][j][2] * inv * silu(bflo(zz.y)), O[dt][j][3] * inv * silu(bfhi(zz.y)));
;       *(uint2*)zp = o;
	v_mov_b32_e32 v8, v242
	v_mov_b32_e32 v9, v243
	v_lshlrev_b32_e32 v12, 16, v8
	v_and_b32_e32 v8, 0xffff0000, v8
	v_mul_f32_e32 v10, 0xbfb8aa3b, v12
	v_mul_f32_e32 v11, 0xbfb8aa3b, v8
	v_exp_f32_e32 v10, v10
	v_exp_f32_e32 v11, v11
	s_nop 0
	v_pk_add_f32 v[10:11], v[10:11], 1.0 op_sel_hi:[1,0]
	s_nop 0
	v_div_scale_f32 v13, s[0:1], v11, v11, v8
	v_rcp_f32_e32 v14, v13
	s_nop 0
	v_fma_f32 v15, -v13, v14, 1.0
	v_fmac_f32_e32 v14, v15, v14
	v_div_scale_f32 v15, vcc, v8, v11, v8
	v_mul_f32_e32 v18, v15, v14
	v_fma_f32 v19, -v13, v18, v15
	v_fmac_f32_e32 v18, v19, v14
	v_fma_f32 v13, -v13, v18, v15
	v_div_fmas_f32 v13, v13, v14, v18
	v_div_fixup_f32 v11, v13, v11, v8
	v_div_scale_f32 v8, s[0:1], v10, v10, v12
	v_rcp_f32_e32 v13, v8
	s_nop 0
	v_fma_f32 v14, -v8, v13, 1.0
	v_fmac_f32_e32 v13, v14, v13
	v_div_scale_f32 v14, vcc, v12, v10, v12
	v_mul_f32_e32 v15, v14, v13
	v_fma_f32 v18, -v8, v15, v14
	v_fmac_f32_e32 v15, v18, v13
	v_fma_f32 v8, -v8, v15, v14
	v_div_fmas_f32 v8, v8, v13, v15
	v_div_fixup_f32 v10, v8, v10, v12
	v_pk_mul_f32 v[4:5], v[4:5], v[10:11]
	v_and_b32_e32 v10, 0xffff0000, v9
	v_cvt_pk_bf16_f32 v4, v4, v5
	v_lshlrev_b32_e32 v5, 16, v9
	v_mul_f32_e32 v8, 0xbfb8aa3b, v5
	v_mul_f32_e32 v9, 0xbfb8aa3b, v10
	v_exp_f32_e32 v8, v8
	v_exp_f32_e32 v9, v9
	s_nop 0
	v_pk_add_f32 v[8:9], v[8:9], 1.0 op_sel_hi:[1,0]
	s_nop 0
	v_div_scale_f32 v11, s[0:1], v9, v9, v10
	v_rcp_f32_e32 v12, v11
	s_nop 0
	v_fma_f32 v13, -v11, v12, 1.0
	v_fmac_f32_e32 v12, v13, v12
	v_div_scale_f32 v13, vcc, v10, v9, v10
	v_mul_f32_e32 v14, v13, v12
	v_fma_f32 v15, -v11, v14, v13
	v_fmac_f32_e32 v14, v15, v12
	v_fma_f32 v11, -v11, v14, v13
	v_div_fmas_f32 v11, v11, v12, v14
	v_div_fixup_f32 v9, v11, v9, v10
	v_div_scale_f32 v10, s[0:1], v8, v8, v5
	v_rcp_f32_e32 v11, v10
	s_nop 0
	v_fma_f32 v12, -v10, v11, 1.0
	v_fmac_f32_e32 v11, v12, v11
	v_div_scale_f32 v12, vcc, v5, v8, v5
	v_mul_f32_e32 v13, v12, v11
	v_fma_f32 v14, -v10, v13, v12
	v_fmac_f32_e32 v13, v14, v11
	v_fma_f32 v10, -v10, v13, v12
	v_div_fmas_f32 v10, v10, v11, v13
	v_div_fixup_f32 v8, v10, v8, v5
	v_pk_mul_f32 v[6:7], v[6:7], v[8:9]
	s_nop 0
	v_cvt_pk_bf16_f32 v5, v6, v7
	global_store_dwordx2 v[16:17], v[4:5], off offset:64
	s_waitcnt vmcnt(3)
	v_mov_b32_e32 v4, v244
	v_mov_b32_e32 v5, v245
	v_lshlrev_b32_e32 v8, 16, v4
	v_and_b32_e32 v4, 0xffff0000, v4
	v_mul_f32_e32 v6, 0xbfb8aa3b, v8
	v_mul_f32_e32 v7, 0xbfb8aa3b, v4
	v_exp_f32_e32 v6, v6
	v_exp_f32_e32 v7, v7
	s_nop 0
	v_pk_add_f32 v[6:7], v[6:7], 1.0 op_sel_hi:[1,0]
	s_nop 0
	v_div_scale_f32 v9, s[0:1], v7, v7, v4
	v_rcp_f32_e32 v10, v9
	s_nop 0
	v_fma_f32 v11, -v9, v10, 1.0
	v_fmac_f32_e32 v10, v11, v10
	v_div_scale_f32 v11, vcc, v4, v7, v4
	v_mul_f32_e32 v12, v11, v10
	v_fma_f32 v13, -v9, v12, v11
	v_fmac_f32_e32 v12, v13, v10
	v_fma_f32 v9, -v9, v12, v11
	v_div_fmas_f32 v9, v9, v10, v12
	v_div_fixup_f32 v7, v9, v7, v4
	v_div_scale_f32 v4, s[0:1], v6, v6, v8
	v_rcp_f32_e32 v9, v4
	s_nop 0
	v_fma_f32 v10, -v4, v9, 1.0
	v_fmac_f32_e32 v9, v10, v9
	v_div_scale_f32 v10, vcc, v8, v6, v8
	v_mul_f32_e32 v11, v10, v9
	v_fma_f32 v12, -v4, v11, v10
	v_fmac_f32_e32 v11, v12, v9
	v_fma_f32 v4, -v4, v11, v10
	v_div_fmas_f32 v4, v4, v9, v11
	v_div_fixup_f32 v6, v4, v6, v8
	v_pk_mul_f32 v[0:1], v[0:1], v[6:7]
	v_and_b32_e32 v6, 0xffff0000, v5
	v_cvt_pk_bf16_f32 v0, v0, v1
	v_lshlrev_b32_e32 v1, 16, v5
	v_mul_f32_e32 v4, 0xbfb8aa3b, v1
	v_mul_f32_e32 v5, 0xbfb8aa3b, v6
	v_exp_f32_e32 v4, v4
	v_exp_f32_e32 v5, v5
	s_nop 0
	v_pk_add_f32 v[4:5], v[4:5], 1.0 op_sel_hi:[1,0]
	s_nop 0
	v_div_scale_f32 v7, s[0:1], v5, v5, v6
	v_rcp_f32_e32 v8, v7
	s_nop 0
	v_fma_f32 v9, -v7, v8, 1.0
	v_fmac_f32_e32 v8, v9, v8
	v_div_scale_f32 v9, vcc, v6, v5, v6
	v_mul_f32_e32 v10, v9, v8
	v_fma_f32 v11, -v7, v10, v9
	v_fmac_f32_e32 v10, v11, v8
	v_fma_f32 v7, -v7, v10, v9
	v_div_fmas_f32 v7, v7, v8, v10
	v_div_fixup_f32 v5, v7, v5, v6
	v_div_scale_f32 v6, s[0:1], v4, v4, v1
	v_rcp_f32_e32 v7, v6
	s_nop 0
	v_fma_f32 v8, -v6, v7, 1.0
	v_fmac_f32_e32 v7, v8, v7
	v_div_scale_f32 v8, vcc, v1, v4, v1
	v_mul_f32_e32 v9, v8, v7
	v_fma_f32 v10, -v6, v9, v8
	v_fmac_f32_e32 v9, v10, v7
	v_fma_f32 v6, -v6, v9, v8
	v_div_fmas_f32 v6, v6, v7, v9
	v_div_fixup_f32 v4, v6, v4, v1
	v_pk_mul_f32 v[2:3], v[2:3], v[4:5]
	s_nop 0
	v_cvt_pk_bf16_f32 v1, v2, v3
	global_store_dwordx2 v[16:17], v[0:1], off offset:96
